# v49 + grid-barrier poll back-off removed (no s_sleep between generation-word polls)
# speedup vs baseline: 1.0065x; 1.0065x over previous
; __global__ void __launch_bounds__(512, 2) fwd_megakernel(Args AV) {
;     ...
;     if (hi > 1000000) cg::this_grid().sync();
.LBB0_12:
	global_load_dword v3, v2, s[4:5] offset:32 sc1
	s_waitcnt vmcnt(0)
	v_and_b32_e32 v3, 0xffff0000, v3
	v_cmp_ne_u32_e32 vcc, v3, v1
	s_or_b64 s[6:7], vcc, s[6:7]
	s_andn2_b64 exec, exec, s[6:7]
	s_cbranch_execnz .LBB0_12

; __device__ __forceinline__ unsigned xb_ld(unsigned* p)              { return __hip_atomic_load(p, __ATOMIC_RELAXED, __HIP_MEMORY_SCOPE_AGENT); }
; __device__ __forceinline__ void xcd_barrier_complete(unsigned* bar, unsigned x, unsigned& nloc, unsigned& nx) {
;     ...
;     for (;;) {
;         sum = 0u; cnt = 0u; mine = 0u;
; #pragma unroll
;         for (unsigned j = 0; j < 16; ++j) { const unsigned c = xb_ld(&bar[XB_XCNT(j)]); sum += c; cnt += (c > 0u) ? 1u : 0u; mine = (j == x) ? c : mine; }
;         if (sum == G) break;
;         __builtin_amdgcn_s_sleep(1);
;         if ((++sp & 255u) == 0u) { if (xb_ld(&bar[XB_TMO])) break; if (sp > XB_SPIN_CAP) { atomicAdd(&bar[XB_TMO], 1u); break; } }
;     }
.LBB0_80:
	global_load_dword v15, v16, s[8:9] sc1
	global_load_dword v0, v16, s[10:11] sc1
	global_load_dword v1, v16, s[12:13] sc1
	global_load_dword v2, v16, s[14:15] sc1
	global_load_dword v3, v16, s[16:17] sc1
	global_load_dword v4, v16, s[18:19] sc1
	global_load_dword v5, v16, s[20:21] sc1
	global_load_dword v6, v16, s[22:23] sc1
	global_load_dword v7, v16, s[24:25] sc1
	global_load_dword v8, v16, s[26:27] sc1
	global_load_dword v9, v16, s[28:29] sc1
	global_load_dword v10, v16, s[30:31] sc1
	global_load_dword v11, v16, s[34:35] sc1
	global_load_dword v12, v16, s[36:37] sc1
	global_load_dword v13, v16, s[40:41] sc1
	global_load_dword v14, v16, s[44:45] sc1
	s_mov_b64 s[48:49], -1
	s_mov_b64 s[38:39], -1
	s_waitcnt vmcnt(14)
	v_add_u32_e32 v17, v0, v15
	s_waitcnt vmcnt(13)
	v_add_u32_e32 v17, v17, v1
	s_waitcnt vmcnt(12)
	v_add_u32_e32 v17, v17, v2
	s_waitcnt vmcnt(11)
	v_add_u32_e32 v17, v17, v3
	s_waitcnt vmcnt(10)
	v_add_u32_e32 v17, v17, v4
	s_waitcnt vmcnt(9)
	v_add_u32_e32 v17, v17, v5
	s_waitcnt vmcnt(8)
	v_add_u32_e32 v17, v17, v6
	s_waitcnt vmcnt(7)
	v_add_u32_e32 v17, v17, v7
	s_waitcnt vmcnt(6)
	v_add_u32_e32 v17, v17, v8
	s_waitcnt vmcnt(5)
	v_add_u32_e32 v17, v17, v9
	s_waitcnt vmcnt(4)
	v_add_u32_e32 v17, v17, v10
	s_waitcnt vmcnt(3)
	v_add_u32_e32 v17, v17, v11
	s_waitcnt vmcnt(2)
	v_add_u32_e32 v17, v17, v12
	s_waitcnt vmcnt(1)
	v_add_u32_e32 v17, v17, v13
	s_waitcnt vmcnt(0)
	v_add_u32_e32 v17, v17, v14
	v_cmp_eq_u32_e32 vcc, s42, v17
	s_cbranch_vccnz .LBB0_79
	s_and_b32 s47, s43, 0xff
	s_cmp_eq_u32 s47, 0
	s_mov_b64 s[50:51], -1
	s_cbranch_scc1 .LBB0_84
	s_and_b64 vcc, exec, s[50:51]
	s_cbranch_vccz .LBB0_79

; __device__ __forceinline__ unsigned xb_ld(unsigned* p)              { return __hip_atomic_load(p, __ATOMIC_RELAXED, __HIP_MEMORY_SCOPE_AGENT); }
; #define XB_SPIN(cond, bar) do { unsigned _sp = 0; while (cond) { __builtin_amdgcn_s_sleep(1); \
;     if ((++_sp & 255u) == 0u) { if (xb_ld(&(bar)[XB_TMO])) break; if (_sp > XB_SPIN_CAP) { atomicAdd(&(bar)[XB_TMO], 1u); break; } } } } while (0)
; __device__ __forceinline__ void xcd_barrier(unsigned* bar, volatile LAS unsigned* st) {
;     ...
;             else XB_SPIN(xb_ld(&bar[XB_TOPGEN]) == tg, bar);
.LBB0_98:
	s_and_b32 s22, s26, 0xff
	s_mov_b64 s[20:21], -1
	s_cmp_lg_u32 s22, 0
	s_mov_b64 s[24:25], -1
	s_cbranch_scc0 .LBB0_101
	s_and_b64 vcc, exec, s[24:25]
	s_cbranch_vccz .LBB0_97

; __device__ __forceinline__ unsigned xb_ld(unsigned* p)              { return __hip_atomic_load(p, __ATOMIC_RELAXED, __HIP_MEMORY_SCOPE_AGENT); }
; #define XB_SPIN(cond, bar) do { unsigned _sp = 0; while (cond) { __builtin_amdgcn_s_sleep(1); \
;     if ((++_sp & 255u) == 0u) { if (xb_ld(&(bar)[XB_TMO])) break; if (_sp > XB_SPIN_CAP) { atomicAdd(&(bar)[XB_TMO], 1u); break; } } } } while (0)
; __device__ __forceinline__ void xcd_barrier(unsigned* bar, volatile LAS unsigned* st) {
;     ...
;             XB_SPIN(xb_ld(&bar[XB_XGEN(x)]) == gen, bar);
.LBB0_115:
	s_and_b32 s18, s24, 0xff
	s_cmp_lg_u32 s18, 0
	s_mov_b64 s[20:21], -1
	s_cbranch_scc0 .LBB0_118
	s_mov_b64 s[22:23], -1
	s_and_b64 vcc, exec, s[20:21]
	s_cbranch_vccz .LBB0_114

; __device__ __forceinline__ unsigned xb_ld(unsigned* p)              { return __hip_atomic_load(p, __ATOMIC_RELAXED, __HIP_MEMORY_SCOPE_AGENT); }
; __device__ __forceinline__ void xcd_barrier_complete(unsigned* bar, unsigned x, unsigned& nloc, unsigned& nx) {
;     ...
;     for (;;) {
;         sum = 0u; cnt = 0u; mine = 0u;
; #pragma unroll
;         for (unsigned j = 0; j < 16; ++j) { const unsigned c = xb_ld(&bar[XB_XCNT(j)]); sum += c; cnt += (c > 0u) ? 1u : 0u; mine = (j == x) ? c : mine; }
;         if (sum == G) break;
;         __builtin_amdgcn_s_sleep(1);
;         if ((++sp & 255u) == 0u) { if (xb_ld(&bar[XB_TMO])) break; if (sp > XB_SPIN_CAP) { atomicAdd(&bar[XB_TMO], 1u); break; } }
;     }
.LBB0_265:
	global_load_dword v15, v195, s[8:9] sc1
	global_load_dword v0, v195, s[10:11] sc1
	global_load_dword v1, v195, s[12:13] sc1
	global_load_dword v2, v195, s[14:15] sc1
	global_load_dword v3, v195, s[16:17] sc1
	global_load_dword v4, v195, s[18:19] sc1
	global_load_dword v5, v195, s[20:21] sc1
	global_load_dword v6, v195, s[22:23] sc1
	global_load_dword v7, v195, s[24:25] sc1
	global_load_dword v8, v195, s[26:27] sc1
	global_load_dword v9, v195, s[28:29] sc1
	global_load_dword v10, v195, s[30:31] sc1
	global_load_dword v11, v195, s[34:35] sc1
	global_load_dword v12, v195, s[36:37] sc1
	global_load_dword v13, v195, s[40:41] sc1
	global_load_dword v14, v195, s[52:53] sc1
	s_mov_b64 s[84:85], -1
	s_mov_b64 s[38:39], -1
	s_waitcnt vmcnt(14)
	v_add_u32_e32 v16, v0, v15
	s_waitcnt vmcnt(13)
	v_add_u32_e32 v16, v16, v1
	s_waitcnt vmcnt(12)
	v_add_u32_e32 v16, v16, v2
	s_waitcnt vmcnt(11)
	v_add_u32_e32 v16, v16, v3
	s_waitcnt vmcnt(10)
	v_add_u32_e32 v16, v16, v4
	s_waitcnt vmcnt(9)
	v_add_u32_e32 v16, v16, v5
	s_waitcnt vmcnt(8)
	v_add_u32_e32 v16, v16, v6
	s_waitcnt vmcnt(7)
	v_add_u32_e32 v16, v16, v7
	s_waitcnt vmcnt(6)
	v_add_u32_e32 v16, v16, v8
	s_waitcnt vmcnt(5)
	v_add_u32_e32 v16, v16, v9
	s_waitcnt vmcnt(4)
	v_add_u32_e32 v16, v16, v10
	s_waitcnt vmcnt(3)
	v_add_u32_e32 v16, v16, v11
	s_waitcnt vmcnt(2)
	v_add_u32_e32 v16, v16, v12
	s_waitcnt vmcnt(1)
	v_add_u32_e32 v16, v16, v13
	s_waitcnt vmcnt(0)
	v_add_u32_e32 v16, v16, v14
	v_cmp_eq_u32_e32 vcc, s88, v16
	s_cbranch_vccnz .LBB0_264
	s_and_b32 s50, s89, 0xff
	s_cmp_eq_u32 s50, 0
	s_mov_b64 s[82:83], -1
	s_cbranch_scc1 .LBB0_269
	s_and_b64 vcc, exec, s[82:83]
	s_cbranch_vccz .LBB0_263

; __device__ __forceinline__ unsigned xb_ld(unsigned* p)              { return __hip_atomic_load(p, __ATOMIC_RELAXED, __HIP_MEMORY_SCOPE_AGENT); }
; #define XB_SPIN(cond, bar) do { unsigned _sp = 0; while (cond) { __builtin_amdgcn_s_sleep(1); \
;     if ((++_sp & 255u) == 0u) { if (xb_ld(&(bar)[XB_TMO])) break; if (_sp > XB_SPIN_CAP) { atomicAdd(&(bar)[XB_TMO], 1u); break; } } } } while (0)
; __device__ __forceinline__ void xcd_barrier(unsigned* bar, volatile LAS unsigned* st) {
;     ...
;             else XB_SPIN(xb_ld(&bar[XB_TOPGEN]) == tg, bar);
.LBB0_300:
	s_and_b32 s20, s24, 0xff
	s_mov_b64 s[18:19], -1
	s_cmp_lg_u32 s20, 0
	s_mov_b64 s[22:23], -1
	s_cbranch_scc0 .LBB0_303
	s_and_b64 vcc, exec, s[22:23]
	s_cbranch_vccz .LBB0_299

; __device__ __forceinline__ unsigned xb_ld(unsigned* p)              { return __hip_atomic_load(p, __ATOMIC_RELAXED, __HIP_MEMORY_SCOPE_AGENT); }
; __device__ __forceinline__ void xcd_barrier_complete(unsigned* bar, unsigned x, unsigned& nloc, unsigned& nx) {
;     ...
;     for (;;) {
;         sum = 0u; cnt = 0u; mine = 0u;
; #pragma unroll
;         for (unsigned j = 0; j < 16; ++j) { const unsigned c = xb_ld(&bar[XB_XCNT(j)]); sum += c; cnt += (c > 0u) ? 1u : 0u; mine = (j == x) ? c : mine; }
;         if (sum == G) break;
;         __builtin_amdgcn_s_sleep(1);
;         if ((++sp & 255u) == 0u) { if (xb_ld(&bar[XB_TMO])) break; if (sp > XB_SPIN_CAP) { atomicAdd(&bar[XB_TMO], 1u); break; } }
;     }
.LBB0_357:
	global_load_dword v15, v195, s[8:9] sc1
	global_load_dword v0, v195, s[10:11] sc1
	global_load_dword v1, v195, s[12:13] sc1
	global_load_dword v2, v195, s[14:15] sc1
	global_load_dword v3, v195, s[16:17] sc1
	global_load_dword v4, v195, s[18:19] sc1
	global_load_dword v5, v195, s[20:21] sc1
	global_load_dword v6, v195, s[22:23] sc1
	global_load_dword v7, v195, s[24:25] sc1
	global_load_dword v8, v195, s[26:27] sc1
	global_load_dword v9, v195, s[28:29] sc1
	global_load_dword v10, v195, s[30:31] sc1
	global_load_dword v11, v195, s[34:35] sc1
	global_load_dword v12, v195, s[36:37] sc1
	global_load_dword v13, v195, s[40:41] sc1
	global_load_dword v14, v195, s[52:53] sc1
	s_mov_b64 s[38:39], -1
	s_mov_b64 s[82:83], -1
	s_waitcnt vmcnt(14)
	v_add_u32_e32 v16, v0, v15
	s_waitcnt vmcnt(13)
	v_add_u32_e32 v16, v16, v1
	s_waitcnt vmcnt(12)
	v_add_u32_e32 v16, v16, v2
	s_waitcnt vmcnt(11)
	v_add_u32_e32 v16, v16, v3
	s_waitcnt vmcnt(10)
	v_add_u32_e32 v16, v16, v4
	s_waitcnt vmcnt(9)
	v_add_u32_e32 v16, v16, v5
	s_waitcnt vmcnt(8)
	v_add_u32_e32 v16, v16, v6
	s_waitcnt vmcnt(7)
	v_add_u32_e32 v16, v16, v7
	s_waitcnt vmcnt(6)
	v_add_u32_e32 v16, v16, v8
	s_waitcnt vmcnt(5)
	v_add_u32_e32 v16, v16, v9
	s_waitcnt vmcnt(4)
	v_add_u32_e32 v16, v16, v10
	s_waitcnt vmcnt(3)
	v_add_u32_e32 v16, v16, v11
	s_waitcnt vmcnt(2)
	v_add_u32_e32 v16, v16, v12
	s_waitcnt vmcnt(1)
	v_add_u32_e32 v16, v16, v13
	s_waitcnt vmcnt(0)
	v_add_u32_e32 v16, v16, v14
	v_cmp_eq_u32_e32 vcc, s88, v16
	s_cbranch_vccnz .LBB0_356
	s_and_b32 s38, s89, 0xff
	s_cmp_eq_u32 s38, 0
	s_mov_b64 s[38:39], -1
	s_mov_b64 vcc, -1
	s_cbranch_scc1 .LBB0_361
	s_and_b64 vcc, exec, vcc
	s_cbranch_vccz .LBB0_356

; __device__ __forceinline__ unsigned xb_ld(unsigned* p)              { return __hip_atomic_load(p, __ATOMIC_RELAXED, __HIP_MEMORY_SCOPE_AGENT); }
; __device__ __forceinline__ void xcd_barrier_complete(unsigned* bar, unsigned x, unsigned& nloc, unsigned& nx) {
;     ...
;     for (;;) {
;         sum = 0u; cnt = 0u; mine = 0u;
; #pragma unroll
;         for (unsigned j = 0; j < 16; ++j) { const unsigned c = xb_ld(&bar[XB_XCNT(j)]); sum += c; cnt += (c > 0u) ? 1u : 0u; mine = (j == x) ? c : mine; }
;         if (sum == G) break;
;         __builtin_amdgcn_s_sleep(1);
;         if ((++sp & 255u) == 0u) { if (xb_ld(&bar[XB_TMO])) break; if (sp > XB_SPIN_CAP) { atomicAdd(&bar[XB_TMO], 1u); break; } }
;     }
.LBB0_701:
	global_load_dword v15, v195, s[8:9] sc1
	global_load_dword v0, v195, s[10:11] sc1
	global_load_dword v1, v195, s[12:13] sc1
	global_load_dword v2, v195, s[14:15] sc1
	global_load_dword v3, v195, s[16:17] sc1
	global_load_dword v4, v195, s[18:19] sc1
	global_load_dword v5, v195, s[20:21] sc1
	global_load_dword v6, v195, s[22:23] sc1
	global_load_dword v7, v195, s[24:25] sc1
	global_load_dword v8, v195, s[26:27] sc1
	global_load_dword v9, v195, s[28:29] sc1
	global_load_dword v10, v195, s[30:31] sc1
	global_load_dword v11, v195, s[34:35] sc1
	global_load_dword v12, v195, s[36:37] sc1
	global_load_dword v13, v195, s[40:41] sc1
	global_load_dword v14, v195, s[52:53] sc1
	s_mov_b64 s[38:39], -1
	s_mov_b64 s[82:83], -1
	s_waitcnt vmcnt(14)
	v_add_u32_e32 v16, v0, v15
	s_waitcnt vmcnt(13)
	v_add_u32_e32 v16, v16, v1
	s_waitcnt vmcnt(12)
	v_add_u32_e32 v16, v16, v2
	s_waitcnt vmcnt(11)
	v_add_u32_e32 v16, v16, v3
	s_waitcnt vmcnt(10)
	v_add_u32_e32 v16, v16, v4
	s_waitcnt vmcnt(9)
	v_add_u32_e32 v16, v16, v5
	s_waitcnt vmcnt(8)
	v_add_u32_e32 v16, v16, v6
	s_waitcnt vmcnt(7)
	v_add_u32_e32 v16, v16, v7
	s_waitcnt vmcnt(6)
	v_add_u32_e32 v16, v16, v8
	s_waitcnt vmcnt(5)
	v_add_u32_e32 v16, v16, v9
	s_waitcnt vmcnt(4)
	v_add_u32_e32 v16, v16, v10
	s_waitcnt vmcnt(3)
	v_add_u32_e32 v16, v16, v11
	s_waitcnt vmcnt(2)
	v_add_u32_e32 v16, v16, v12
	s_waitcnt vmcnt(1)
	v_add_u32_e32 v16, v16, v13
	s_waitcnt vmcnt(0)
	v_add_u32_e32 v16, v16, v14
	v_cmp_eq_u32_e32 vcc, s86, v16
	s_cbranch_vccnz .LBB0_700
	s_and_b32 s38, s88, 0xff
	s_cmp_eq_u32 s38, 0
	s_mov_b64 s[38:39], -1
	s_mov_b64 vcc, -1
	s_cbranch_scc1 .LBB0_705
	s_and_b64 vcc, exec, vcc
	s_cbranch_vccz .LBB0_700

; __device__ __forceinline__ unsigned xb_ld(unsigned* p)              { return __hip_atomic_load(p, __ATOMIC_RELAXED, __HIP_MEMORY_SCOPE_AGENT); }
; __device__ __forceinline__ void xcd_barrier_complete(unsigned* bar, unsigned x, unsigned& nloc, unsigned& nx) {
;     ...
;     for (;;) {
;         sum = 0u; cnt = 0u; mine = 0u;
; #pragma unroll
;         for (unsigned j = 0; j < 16; ++j) { const unsigned c = xb_ld(&bar[XB_XCNT(j)]); sum += c; cnt += (c > 0u) ? 1u : 0u; mine = (j == x) ? c : mine; }
;         if (sum == G) break;
;         __builtin_amdgcn_s_sleep(1);
;         if ((++sp & 255u) == 0u) { if (xb_ld(&bar[XB_TMO])) break; if (sp > XB_SPIN_CAP) { atomicAdd(&bar[XB_TMO], 1u); break; } }
;     }
.LBB0_1039:
	global_load_dword v15, v195, s[8:9] sc1
	global_load_dword v0, v195, s[10:11] sc1
	global_load_dword v1, v195, s[12:13] sc1
	global_load_dword v2, v195, s[14:15] sc1
	global_load_dword v3, v195, s[16:17] sc1
	global_load_dword v4, v195, s[18:19] sc1
	global_load_dword v5, v195, s[20:21] sc1
	global_load_dword v6, v195, s[22:23] sc1
	global_load_dword v7, v195, s[24:25] sc1
	global_load_dword v8, v195, s[26:27] sc1
	global_load_dword v9, v195, s[28:29] sc1
	global_load_dword v10, v195, s[30:31] sc1
	global_load_dword v11, v195, s[34:35] sc1
	global_load_dword v12, v195, s[36:37] sc1
	global_load_dword v13, v195, s[40:41] sc1
	global_load_dword v14, v195, s[52:53] sc1
	s_mov_b64 s[38:39], -1
	s_mov_b64 s[82:83], -1
	s_waitcnt vmcnt(14)
	v_add_u32_e32 v16, v0, v15
	s_waitcnt vmcnt(13)
	v_add_u32_e32 v16, v16, v1
	s_waitcnt vmcnt(12)
	v_add_u32_e32 v16, v16, v2
	s_waitcnt vmcnt(11)
	v_add_u32_e32 v16, v16, v3
	s_waitcnt vmcnt(10)
	v_add_u32_e32 v16, v16, v4
	s_waitcnt vmcnt(9)
	v_add_u32_e32 v16, v16, v5
	s_waitcnt vmcnt(8)
	v_add_u32_e32 v16, v16, v6
	s_waitcnt vmcnt(7)
	v_add_u32_e32 v16, v16, v7
	s_waitcnt vmcnt(6)
	v_add_u32_e32 v16, v16, v8
	s_waitcnt vmcnt(5)
	v_add_u32_e32 v16, v16, v9
	s_waitcnt vmcnt(4)
	v_add_u32_e32 v16, v16, v10
	s_waitcnt vmcnt(3)
	v_add_u32_e32 v16, v16, v11
	s_waitcnt vmcnt(2)
	v_add_u32_e32 v16, v16, v12
	s_waitcnt vmcnt(1)
	v_add_u32_e32 v16, v16, v13
	s_waitcnt vmcnt(0)
	v_add_u32_e32 v16, v16, v14
	v_cmp_eq_u32_e32 vcc, s81, v16
	s_cbranch_vccnz .LBB0_1038
	s_and_b32 s38, s86, 0xff
	s_cmp_eq_u32 s38, 0
	s_mov_b64 s[38:39], -1
	s_mov_b64 s[88:89], -1
	s_cbranch_scc1 .LBB0_1043
	s_and_b64 vcc, exec, s[88:89]
	s_cbranch_vccz .LBB0_1037
